# P0a transposer: tile index = wave*G + bid so the 6th-round tiles spread over all CUs instead of the first 112 workgroups
# baseline (speedup 1.0000x reference)
; __device__ __forceinline__ void transpose_job(const float* W, int ldw, int K, int N, const float* g, bf16_t* WT, float* scr, int& base, int gwave, int gwaves, int lane) {
;     const int nitems = (K / 64) * (N / 32);
;     int start = (gwave - (base % gwaves) + gwaves) % gwaves;
;     int it = start;
; __global__ void __launch_bounds__(512, 2) fwd_kernel(Params p) {
;     ...
;     const int tid = threadIdx.x, lane = tid & 63, wave = __builtin_amdgcn_readfirstlane(tid >> 6);
;     const int G = gridDim.x, bid = blockIdx.x, gtid = bid * 512 + tid, gthreads = G * 512, gwave = bid * 8 + wave, gwaves = G * 8;
;     unsigned char* ws = p.ws;
;     bf16_t* WT = (bf16_t*)(ws + OFF_WT); bf16_t* xb = (bf16_t*)(ws + OFF_XB); bf16_t* Qn = (bf16_t*)p.out;     float* ss = (float*)(ws + OFF_SS);
;     bf16_t* memb = (bf16_t*)(ws + OFF_MEMB); float* ssm = (float*)(ws + OFF_SSM); bf16_t* memKV = (bf16_t*)(ws + OFF_MEMKV);
;     float* cosT = (float*)(ws + OFF_ROPE); float* sinT = cosT + (size_t)SEQ * 32; float* kmean = (float*)(ws + OFF_KMEAN); int* cntAll = (int*)(ws + OFF_CNT);
;     bf16_t* H = (bf16_t*)(ws + OFF_H); float* Wtmp = (float*)(ws + OFF_H); bf16_t* AO = (bf16_t*)(ws + OFF_AO); bf16_t* Kimg = (bf16_t*)(ws + OFF_KIMG); bf16_t* VT = (bf16_t*)(ws + OFF_VT);
;     unsigned short* lists = (unsigned short*)(ws + OFF_LIST); bf16_t* ACT = (bf16_t*)(ws + OFF_ACT); bf16_t* Opart = (bf16_t*)(ws + OFF_OPART); float* lse = (float*)(ws + OFF_LSE);
;     const float* x_in = p.in[0]; const float* mem = p.in[1]; const float* g_mix = p.in[2]; const float* g_mem = p.in[3]; const float* g_mlp = p.in[4];
;     const float* w_in_pool = p.in[5]; const float* w_pool_group = p.in[6]; const float* pool_scale = p.in[7]; const float* w_in_moba = p.in[8];
;     const float* moba_q_gain = p.in[9]; const float* moba_k_gain = p.in[10]; const float* w_mem_kv = p.in[11]; const float* mem_q_gain = p.in[12]; const float* mem_k_gain = p.in[13];
;     const float* w_out = p.in[14]; const float* w_ff1 = p.in[15]; const float* w_ff2 = p.in[16];
;     float* xres = p.out;
;     const int vcu = (G % 8 == 0) ? (bid % 8) * (G / 8) + bid / 8 : bid;
;     const int lo = p.ph_lo, hi = p.ph_hi;
;     int ph = 0;
;     if (lo < 0) grid.sync();
.LBB0_7:
	s_or_b64 exec, exec, s[2:3]
	v_readlane_b32 s4, v252, 0
	s_lshr_b32 s33, s10, 6
	s_lshl_b32 s54, s4, 3
	s_lshl_b32 s70, s68, 9
	s_add_i32 s10, s33, s54
	s_lshl_b32 s30, s68, 3
	s_load_dwordx16 s[12:27], s[0:1], 0x0
	s_load_dwordx16 s[76:91], s[0:1], 0x40
	s_add_u32 s0, s64, 0xa368000
	s_addc_u32 s1, s65, 0
	v_writelane_b32 v252, s0, 4
	s_cmp_lt_i32 s66, 1
	v_and_b32_e32 v148, 63, v204
	v_writelane_b32 v252, s1, 5
	s_cselect_b64 s[0:1], -1, 0
	s_cmp_gt_i32 s67, 0
	s_cselect_b64 s[2:3], -1, 0
	s_and_b64 s[0:1], s[0:1], s[2:3]
	s_andn2_b64 vcc, exec, s[0:1]
	v_lshl_add_u32 v136, s4, 9, v204
	s_cbranch_vccnz .LBB0_320
	s_waitcnt lgkmcnt(0)
	v_lshrrev_b32_e32 v160, 4, v148
	v_and_b32_e32 v161, 15, v148
	v_lshlrev_b32_e32 v161, 4, v161
	v_and_b32_e32 v163, 7, v148
	v_lshlrev_b32_e32 v165, 5, v163
	v_lshrrev_b32_e32 v164, 3, v148
	s_mul_i32 s40, s33, 0x4100
	s_movk_i32 s41, 0x104
	v_mad_u32_u24 v157, v160, s41, v161
	v_add_u32_e32 v157, s40, v157
	s_movk_i32 s41, 0x820
	v_lshlrev_b32_e32 v158, 2, v164
	v_mad_u32_u24 v158, v163, s41, v158
	v_add_u32_e32 v158, s40, v158
	v_lshlrev_b32_e32 v163, 4, v163
	s_lshr_b32 s34, s54, 3
	s_mul_i32 s35, s33, s68
	s_add_u32 s34, s34, s35
